# gate GEMM epilogue de-serialised the same way: the four distinct bias pieces loaded once per tile, per-group loads and waits removed
# speedup vs baseline: 1.4691x; 1.0003x over previous
; __device__ __forceinline__ unsigned pk2(float lo, float hi) { return f2bf(lo) | (f2bf(hi) << 16); }
;     __device__ __forceinline__ void operator()(const f32x4 (&acc)[2][2][4][2], const pg8::Unit& u, int wr, int wc, int fr, int fq) const {
;     ...
;                     } else if constexpr (MODE == 1) {
;                         const f32x4 b0 = *(const f32x4*)(vec + col), b1 = *(const f32x4*)(vec + col + 4);
;                         float r[8];
; #pragma unroll
;                         for (int i = 0; i < 4; ++i) { r[i] = 1.f / (1.f + __expf(-(v0[i] + b0[i]))); r[4 + i] = 1.f / (1.f + __expf(-(v1[i] + b1[i]))); }
;                         u32x4 w; w.x = pk2(r[0], r[1]); w.y = pk2(r[2], r[3]); w.z = pk2(r[4], r[5]); w.w = pk2(r[6], r[7]);
;                         *(u32x4*)(ob + row * 4096 + col) = w;
.LBB0_1125:
	v_lshl_or_b32 v2, s8, 8, v214
	v_ashrrev_i32_e32 v3, 31, v2
	v_lshl_add_u64 v[0:1], v[2:3], 2, s[4:5]
	global_load_dwordx4 v[226:229], v[0:1], off offset:16
	global_load_dwordx4 v[230:233], v[0:1], off
	global_load_dwordx4 v[234:237], v[0:1], off offset:528
	global_load_dwordx4 v[238:241], v[0:1], off offset:512
	s_nop 15
	s_nop 15
	v_lshl_add_u32 v4, s9, 8, v203
	v_ashrrev_i32_e32 v5, 31, v4
	v_lshlrev_b64 v[6:7], 13, v[4:5]
	s_mov_b64 s[10:11], -1
	s_waitcnt vmcnt(0)
	v_fmamk_f32 v13, v155, 0x3c800000, v229
	v_fmamk_f32 v5, v156, 0x3c800000, v230
	v_mul_f32_e32 v5, 0xbfb8aa3b, v5
	v_exp_f32_e32 v14, v5
	v_fmamk_f32 v5, v152, 0x3c800000, v226
	v_mul_f32_e32 v5, 0xbfb8aa3b, v5
	v_exp_f32_e32 v10, v5
	v_fmamk_f32 v5, v157, 0x3c800000, v231
	v_mul_f32_e32 v5, 0xbfb8aa3b, v5
	v_exp_f32_e32 v18, v5
	v_fmamk_f32 v5, v153, 0x3c800000, v227
	v_mul_f32_e32 v5, 0xbfb8aa3b, v5
	v_exp_f32_e32 v8, v5
	v_fmamk_f32 v5, v158, 0x3c800000, v232
	v_mul_f32_e32 v5, 0xbfb8aa3b, v5
	v_exp_f32_e32 v15, v5
	v_fmamk_f32 v5, v154, 0x3c800000, v228
	v_mul_f32_e32 v5, 0xbfb8aa3b, v5
	v_fmamk_f32 v17, v159, 0x3c800000, v233
	v_exp_f32_e32 v11, v5
	v_mul_f32_e32 v5, 0xbfb8aa3b, v17
	v_exp_f32_e32 v19, v5
	v_mul_f32_e32 v5, 0xbfb8aa3b, v13
	v_pk_add_f32 v[12:13], v[14:15], 1.0 op_sel_hi:[1,0]
	v_exp_f32_e32 v9, v5
	v_pk_add_f32 v[10:11], v[10:11], 1.0 op_sel_hi:[1,0]
	v_pk_add_f32 v[8:9], v[8:9], 1.0 op_sel_hi:[1,0]
	v_rcp_f32_e32 v5, v13
	v_pk_add_f32 v[14:15], v[18:19], 1.0 op_sel_hi:[1,0]
	v_rcp_f32_e32 v12, v12
	v_rcp_f32_e32 v13, v14
	v_rcp_f32_e32 v14, v15
	v_rcp_f32_e32 v11, v11
	v_rcp_f32_e32 v10, v10
	v_rcp_f32_e32 v8, v8
	v_rcp_f32_e32 v9, v9
	v_cvt_pk_bf16_f32 v10, v10, v8
	v_cvt_pk_bf16_f32 v8, v12, v13
	v_lshl_add_u64 v[12:13], s[24:25], 0, v[6:7]
	v_lshlrev_b64 v[6:7], 1, v[2:3]
	v_cvt_pk_bf16_f32 v11, v11, v9
	v_cvt_pk_bf16_f32 v9, v5, v14
	v_lshl_add_u64 v[2:3], v[12:13], 0, v[6:7]
	global_store_dwordx4 v[2:3], v[8:11], off
	s_nop 0
	v_fmamk_f32 v13, v147, 0x3c800000, v237
	v_fmamk_f32 v5, v148, 0x3c800000, v238
	v_mul_f32_e32 v5, 0xbfb8aa3b, v5
	v_exp_f32_e32 v14, v5
	v_fmamk_f32 v5, v144, 0x3c800000, v234
	v_mul_f32_e32 v5, 0xbfb8aa3b, v5
	v_exp_f32_e32 v10, v5
	v_fmamk_f32 v5, v149, 0x3c800000, v239
	v_mul_f32_e32 v5, 0xbfb8aa3b, v5
	v_exp_f32_e32 v18, v5
	v_fmamk_f32 v5, v145, 0x3c800000, v235
	v_mul_f32_e32 v5, 0xbfb8aa3b, v5
	v_exp_f32_e32 v8, v5
	v_fmamk_f32 v5, v150, 0x3c800000, v240
	v_mul_f32_e32 v5, 0xbfb8aa3b, v5
	v_exp_f32_e32 v15, v5
	v_fmamk_f32 v5, v146, 0x3c800000, v236
	v_mul_f32_e32 v5, 0xbfb8aa3b, v5
	v_fmamk_f32 v17, v151, 0x3c800000, v241
	v_exp_f32_e32 v11, v5
	v_mul_f32_e32 v5, 0xbfb8aa3b, v17
	v_exp_f32_e32 v19, v5
	v_mul_f32_e32 v5, 0xbfb8aa3b, v13
	v_pk_add_f32 v[12:13], v[14:15], 1.0 op_sel_hi:[1,0]
	v_exp_f32_e32 v9, v5
	v_pk_add_f32 v[10:11], v[10:11], 1.0 op_sel_hi:[1,0]
	v_pk_add_f32 v[8:9], v[8:9], 1.0 op_sel_hi:[1,0]
	v_rcp_f32_e32 v5, v13
	v_rcp_f32_e32 v14, v12
	v_pk_add_f32 v[12:13], v[18:19], 1.0 op_sel_hi:[1,0]
	s_nop 0
	v_rcp_f32_e32 v12, v12
	v_rcp_f32_e32 v13, v13
	v_rcp_f32_e32 v11, v11
	v_rcp_f32_e32 v10, v10
	v_rcp_f32_e32 v8, v8
	v_rcp_f32_e32 v9, v9
	s_nop 0
	v_cvt_pk_bf16_f32 v11, v11, v9
	v_cvt_pk_bf16_f32 v10, v10, v8
	v_cvt_pk_bf16_f32 v9, v5, v13
	v_cvt_pk_bf16_f32 v8, v14, v12
	global_store_dwordx4 v[2:3], v[8:11], off offset:256
	s_nop 1
	s_nop 0
	v_or_b32_e32 v8, 16, v4
	v_ashrrev_i32_e32 v9, 31, v8
	v_lshlrev_b64 v[8:9], 13, v[8:9]
	v_lshl_add_u64 v[8:9], s[24:25], 0, v[8:9]
	v_lshl_add_u64 v[8:9], v[8:9], 0, v[6:7]
	v_fmamk_f32 v13, v139, 0x3c800000, v229
	v_fmamk_f32 v5, v140, 0x3c800000, v230
	v_mul_f32_e32 v5, 0xbfb8aa3b, v5
	v_exp_f32_e32 v14, v5
	v_fmamk_f32 v5, v136, 0x3c800000, v226
	v_mul_f32_e32 v5, 0xbfb8aa3b, v5
	v_exp_f32_e32 v18, v5
	v_fmamk_f32 v5, v141, 0x3c800000, v231
	v_mul_f32_e32 v5, 0xbfb8aa3b, v5
	v_exp_f32_e32 v20, v5
	v_fmamk_f32 v5, v137, 0x3c800000, v227
	v_mul_f32_e32 v5, 0xbfb8aa3b, v5
	v_exp_f32_e32 v10, v5
	v_fmamk_f32 v5, v142, 0x3c800000, v232
	v_mul_f32_e32 v5, 0xbfb8aa3b, v5
	v_exp_f32_e32 v15, v5
	v_fmamk_f32 v5, v138, 0x3c800000, v228
	v_mul_f32_e32 v5, 0xbfb8aa3b, v5
	v_fmamk_f32 v17, v143, 0x3c800000, v233
	v_exp_f32_e32 v19, v5
	v_mul_f32_e32 v5, 0xbfb8aa3b, v17
	v_exp_f32_e32 v21, v5
	v_mul_f32_e32 v5, 0xbfb8aa3b, v13
	v_pk_add_f32 v[12:13], v[14:15], 1.0 op_sel_hi:[1,0]
	v_exp_f32_e32 v11, v5
	s_nop 0
	v_pk_add_f32 v[10:11], v[10:11], 1.0 op_sel_hi:[1,0]
	v_rcp_f32_e32 v5, v13
	v_rcp_f32_e32 v14, v12
	v_pk_add_f32 v[12:13], v[20:21], 1.0 op_sel_hi:[1,0]
	s_nop 0
	v_rcp_f32_e32 v15, v12
	v_rcp_f32_e32 v16, v13
	v_pk_add_f32 v[12:13], v[18:19], 1.0 op_sel_hi:[1,0]
	s_nop 0
	v_rcp_f32_e32 v13, v13
	v_rcp_f32_e32 v12, v12
	v_rcp_f32_e32 v10, v10
	v_rcp_f32_e32 v11, v11
	s_nop 0
	v_cvt_pk_bf16_f32 v13, v13, v11
	v_cvt_pk_bf16_f32 v12, v12, v10
	v_cvt_pk_bf16_f32 v11, v5, v16
	v_cvt_pk_bf16_f32 v10, v14, v15
	global_store_dwordx4 v[8:9], v[10:13], off
	s_nop 1
	s_nop 0
	v_fmamk_f32 v13, v131, 0x3c800000, v237
	v_fmamk_f32 v5, v132, 0x3c800000, v238
	v_mul_f32_e32 v5, 0xbfb8aa3b, v5
	v_exp_f32_e32 v14, v5
	v_fmamk_f32 v5, v128, 0x3c800000, v234
	v_mul_f32_e32 v5, 0xbfb8aa3b, v5
	v_exp_f32_e32 v18, v5
	v_fmamk_f32 v5, v133, 0x3c800000, v239
	v_mul_f32_e32 v5, 0xbfb8aa3b, v5
	v_exp_f32_e32 v20, v5
	v_fmamk_f32 v5, v129, 0x3c800000, v235
	v_mul_f32_e32 v5, 0xbfb8aa3b, v5
	v_exp_f32_e32 v10, v5
	v_fmamk_f32 v5, v134, 0x3c800000, v240
	v_mul_f32_e32 v5, 0xbfb8aa3b, v5
	v_exp_f32_e32 v15, v5
	v_fmamk_f32 v5, v130, 0x3c800000, v236
	v_mul_f32_e32 v5, 0xbfb8aa3b, v5
	v_fmamk_f32 v17, v135, 0x3c800000, v241
	v_exp_f32_e32 v19, v5
	v_mul_f32_e32 v5, 0xbfb8aa3b, v17
; __device__ __forceinline__ unsigned pk2(float lo, float hi) { return f2bf(lo) | (f2bf(hi) << 16); }
;     __device__ __forceinline__ void operator()(const f32x4 (&acc)[2][2][4][2], const pg8::Unit& u, int wr, int wc, int fr, int fq) const {
;     ...
;                     } else if constexpr (MODE == 1) {
;                         const f32x4 b0 = *(const f32x4*)(vec + col), b1 = *(const f32x4*)(vec + col + 4);
;                         float r[8];
; #pragma unroll
;                         for (int i = 0; i < 4; ++i) { r[i] = 1.f / (1.f + __expf(-(v0[i] + b0[i]))); r[4 + i] = 1.f / (1.f + __expf(-(v1[i] + b1[i]))); }
;                         u32x4 w; w.x = pk2(r[0], r[1]); w.y = pk2(r[2], r[3]); w.z = pk2(r[4], r[5]); w.w = pk2(r[6], r[7]);
;                         *(u32x4*)(ob + row * 4096 + col) = w;
	v_exp_f32_e32 v21, v5
	v_mul_f32_e32 v5, 0xbfb8aa3b, v13
	v_pk_add_f32 v[12:13], v[14:15], 1.0 op_sel_hi:[1,0]
	v_exp_f32_e32 v11, v5
	s_nop 0
	v_pk_add_f32 v[10:11], v[10:11], 1.0 op_sel_hi:[1,0]
	v_rcp_f32_e32 v5, v13
	v_rcp_f32_e32 v14, v12
	v_pk_add_f32 v[12:13], v[20:21], 1.0 op_sel_hi:[1,0]
	s_nop 0
	v_rcp_f32_e32 v15, v12
	v_rcp_f32_e32 v16, v13
	v_pk_add_f32 v[12:13], v[18:19], 1.0 op_sel_hi:[1,0]
	s_nop 0
	v_rcp_f32_e32 v13, v13
	v_rcp_f32_e32 v12, v12
	v_rcp_f32_e32 v10, v10
	v_rcp_f32_e32 v11, v11
	s_nop 0
	v_cvt_pk_bf16_f32 v13, v13, v11
	v_cvt_pk_bf16_f32 v12, v12, v10
	v_cvt_pk_bf16_f32 v11, v5, v16
	v_cvt_pk_bf16_f32 v10, v14, v15
	global_store_dwordx4 v[8:9], v[10:13], off offset:256
	s_nop 0
	v_or_b32_e32 v8, 32, v4
	v_ashrrev_i32_e32 v9, 31, v8
	v_lshlrev_b64 v[8:9], 13, v[8:9]
	v_lshl_add_u64 v[8:9], s[24:25], 0, v[8:9]
	v_lshl_add_u64 v[8:9], v[8:9], 0, v[6:7]
	v_or_b32_e32 v4, 48, v4
	v_fmamk_f32 v13, v123, 0x3c800000, v229
	v_fmamk_f32 v5, v124, 0x3c800000, v230
	v_mul_f32_e32 v5, 0xbfb8aa3b, v5
	v_exp_f32_e32 v14, v5
	v_fmamk_f32 v5, v120, 0x3c800000, v226
	v_mul_f32_e32 v5, 0xbfb8aa3b, v5
	v_exp_f32_e32 v18, v5
	v_fmamk_f32 v5, v125, 0x3c800000, v231
	v_mul_f32_e32 v5, 0xbfb8aa3b, v5
	v_exp_f32_e32 v20, v5
	v_fmamk_f32 v5, v121, 0x3c800000, v227
	v_mul_f32_e32 v5, 0xbfb8aa3b, v5
	v_exp_f32_e32 v10, v5
	v_fmamk_f32 v5, v126, 0x3c800000, v232
	v_mul_f32_e32 v5, 0xbfb8aa3b, v5
	v_exp_f32_e32 v15, v5
	v_fmamk_f32 v5, v122, 0x3c800000, v228
	v_mul_f32_e32 v5, 0xbfb8aa3b, v5
	v_fmamk_f32 v17, v127, 0x3c800000, v233
	v_exp_f32_e32 v19, v5
	v_mul_f32_e32 v5, 0xbfb8aa3b, v17
	v_exp_f32_e32 v21, v5
	v_mul_f32_e32 v5, 0xbfb8aa3b, v13
	v_pk_add_f32 v[12:13], v[14:15], 1.0 op_sel_hi:[1,0]
	v_exp_f32_e32 v11, v5
	s_nop 0
	v_pk_add_f32 v[10:11], v[10:11], 1.0 op_sel_hi:[1,0]
	v_rcp_f32_e32 v5, v13
	v_rcp_f32_e32 v14, v12
	v_pk_add_f32 v[12:13], v[20:21], 1.0 op_sel_hi:[1,0]
	s_nop 0
	v_rcp_f32_e32 v15, v12
	v_rcp_f32_e32 v16, v13
	v_pk_add_f32 v[12:13], v[18:19], 1.0 op_sel_hi:[1,0]
	s_nop 0
	v_rcp_f32_e32 v13, v13
	v_rcp_f32_e32 v12, v12
	v_rcp_f32_e32 v10, v10
	v_rcp_f32_e32 v11, v11
	s_nop 0
	v_cvt_pk_bf16_f32 v13, v13, v11
	v_cvt_pk_bf16_f32 v12, v12, v10
	v_cvt_pk_bf16_f32 v11, v5, v16
	v_cvt_pk_bf16_f32 v10, v14, v15
	global_store_dwordx4 v[8:9], v[10:13], off
	s_nop 1
	s_nop 0
	v_fmamk_f32 v13, v115, 0x3c800000, v237
	v_fmamk_f32 v5, v116, 0x3c800000, v238
	v_mul_f32_e32 v5, 0xbfb8aa3b, v5
	v_exp_f32_e32 v14, v5
	v_fmamk_f32 v5, v112, 0x3c800000, v234
	v_mul_f32_e32 v5, 0xbfb8aa3b, v5
	v_exp_f32_e32 v18, v5
	v_fmamk_f32 v5, v117, 0x3c800000, v239
	v_mul_f32_e32 v5, 0xbfb8aa3b, v5
	v_exp_f32_e32 v20, v5
	v_fmamk_f32 v5, v113, 0x3c800000, v235
	v_mul_f32_e32 v5, 0xbfb8aa3b, v5
	v_exp_f32_e32 v10, v5
	v_fmamk_f32 v5, v118, 0x3c800000, v240
	v_mul_f32_e32 v5, 0xbfb8aa3b, v5
	v_exp_f32_e32 v15, v5
	v_fmamk_f32 v5, v114, 0x3c800000, v236
	v_mul_f32_e32 v5, 0xbfb8aa3b, v5
	v_fmamk_f32 v17, v119, 0x3c800000, v241
	v_exp_f32_e32 v19, v5
	v_mul_f32_e32 v5, 0xbfb8aa3b, v17
	v_exp_f32_e32 v21, v5
	v_mul_f32_e32 v5, 0xbfb8aa3b, v13
	v_pk_add_f32 v[12:13], v[14:15], 1.0 op_sel_hi:[1,0]
	v_exp_f32_e32 v11, v5
	s_nop 0
	v_pk_add_f32 v[10:11], v[10:11], 1.0 op_sel_hi:[1,0]
	v_rcp_f32_e32 v5, v13
	v_rcp_f32_e32 v14, v12
	v_pk_add_f32 v[12:13], v[20:21], 1.0 op_sel_hi:[1,0]
	s_nop 0
	v_rcp_f32_e32 v15, v12
	v_rcp_f32_e32 v16, v13
	v_pk_add_f32 v[12:13], v[18:19], 1.0 op_sel_hi:[1,0]
	s_nop 0
	v_rcp_f32_e32 v13, v13
	v_rcp_f32_e32 v12, v12
	v_rcp_f32_e32 v10, v10
	v_div_scale_f32 v17, s[8:9], v11, v11, 1.0
	v_rcp_f32_e32 v18, v17
	s_nop 0
	v_fma_f32 v19, -v17, v18, 1.0
	v_fmac_f32_e32 v18, v19, v18
	v_div_scale_f32 v19, vcc, 1.0, v11, 1.0
	v_mul_f32_e32 v20, v19, v18
	v_fma_f32 v21, -v17, v20, v19
	v_rcp_f32_e32 v11, v11
	s_nop 0
	v_cvt_pk_bf16_f32 v13, v13, v11
	v_cvt_pk_bf16_f32 v12, v12, v10
	v_cvt_pk_bf16_f32 v11, v5, v16
	v_cvt_pk_bf16_f32 v10, v14, v15
	global_store_dwordx4 v[8:9], v[10:13], off offset:256
	s_nop 0
	v_ashrrev_i32_e32 v5, 31, v4
	v_lshlrev_b64 v[4:5], 13, v[4:5]
	v_lshl_add_u64 v[4:5], s[24:25], 0, v[4:5]
	v_lshl_add_u64 v[4:5], v[4:5], 0, v[6:7]
	v_fmamk_f32 v8, v104, 0x3c800000, v226
	v_mul_f32_e32 v8, 0xbfb8aa3b, v8
	v_exp_f32_e32 v16, v8
	v_fmamk_f32 v8, v109, 0x3c800000, v231
	v_mul_f32_e32 v8, 0xbfb8aa3b, v8
	v_fmamk_f32 v12, v108, 0x3c800000, v230
	v_exp_f32_e32 v18, v8
	v_fmamk_f32 v8, v105, 0x3c800000, v227
	v_fmamk_f32 v9, v110, 0x3c800000, v232
	v_mul_f32_e32 v12, 0xbfb8aa3b, v12
	v_mul_f32_e32 v9, 0xbfb8aa3b, v9
	v_exp_f32_e32 v12, v12
	v_exp_f32_e32 v13, v9
	v_fmamk_f32 v9, v106, 0x3c800000, v228
	v_mul_f32_e32 v9, 0xbfb8aa3b, v9
	v_fmamk_f32 v15, v111, 0x3c800000, v233
	v_exp_f32_e32 v17, v9
	v_mul_f32_e32 v9, 0xbfb8aa3b, v15
	v_fmamk_f32 v11, v107, 0x3c800000, v229
	v_exp_f32_e32 v19, v9
	v_mul_f32_e32 v9, 0xbfb8aa3b, v11
	v_pk_add_f32 v[10:11], v[12:13], 1.0 op_sel_hi:[1,0]
	v_mul_f32_e32 v8, 0xbfb8aa3b, v8
	v_exp_f32_e32 v8, v8
	v_exp_f32_e32 v9, v9
	v_rcp_f32_e32 v12, v11
	v_pk_add_f32 v[8:9], v[8:9], 1.0 op_sel_hi:[1,0]
	v_rcp_f32_e32 v13, v10
	v_pk_add_f32 v[10:11], v[18:19], 1.0 op_sel_hi:[1,0]
	s_nop 0
	v_rcp_f32_e32 v14, v10
	v_rcp_f32_e32 v15, v11
	v_pk_add_f32 v[10:11], v[16:17], 1.0 op_sel_hi:[1,0]
	s_nop 0
	v_rcp_f32_e32 v11, v11
	v_rcp_f32_e32 v10, v10
	v_rcp_f32_e32 v8, v8
	v_div_scale_f32 v16, s[8:9], v9, v9, 1.0
	v_rcp_f32_e32 v17, v16
	s_nop 0
	v_fma_f32 v18, -v16, v17, 1.0
	v_fmac_f32_e32 v17, v18, v17
	v_div_scale_f32 v18, vcc, 1.0, v9, 1.0
	v_mul_f32_e32 v19, v18, v17
	v_fma_f32 v20, -v16, v19, v18
	v_fmac_f32_e32 v19, v20, v17
	v_rcp_f32_e32 v9, v9
	s_nop 0
	v_cvt_pk_bf16_f32 v11, v11, v9
; __device__ __forceinline__ unsigned pk2(float lo, float hi) { return f2bf(lo) | (f2bf(hi) << 16); }
;     __device__ __forceinline__ void operator()(const f32x4 (&acc)[2][2][4][2], const pg8::Unit& u, int wr, int wc, int fr, int fq) const {
;     ...
;                     } else if constexpr (MODE == 1) {
;                         const f32x4 b0 = *(const f32x4*)(vec + col), b1 = *(const f32x4*)(vec + col + 4);
;                         float r[8];
; #pragma unroll
;                         for (int i = 0; i < 4; ++i) { r[i] = 1.f / (1.f + __expf(-(v0[i] + b0[i]))); r[4 + i] = 1.f / (1.f + __expf(-(v1[i] + b1[i]))); }
;                         u32x4 w; w.x = pk2(r[0], r[1]); w.y = pk2(r[2], r[3]); w.z = pk2(r[4], r[5]); w.w = pk2(r[6], r[7]);
;                         *(u32x4*)(ob + row * 4096 + col) = w;
	v_cvt_pk_bf16_f32 v10, v10, v8
	v_cvt_pk_bf16_f32 v9, v12, v15
	v_cvt_pk_bf16_f32 v8, v13, v14
	global_store_dwordx4 v[4:5], v[8:11], off
	s_nop 0
	v_fmamk_f32 v6, v96, 0x3c800000, v234
	v_mul_f32_e32 v6, 0xbfb8aa3b, v6
	v_exp_f32_e32 v14, v6
	v_fmamk_f32 v6, v101, 0x3c800000, v239
	v_mul_f32_e32 v6, 0xbfb8aa3b, v6
	v_fmamk_f32 v10, v100, 0x3c800000, v238
	v_exp_f32_e32 v16, v6
	v_fmamk_f32 v6, v97, 0x3c800000, v235
	v_fmamk_f32 v7, v102, 0x3c800000, v240
	v_mul_f32_e32 v10, 0xbfb8aa3b, v10
	v_mul_f32_e32 v7, 0xbfb8aa3b, v7
	v_exp_f32_e32 v10, v10
	v_exp_f32_e32 v11, v7
	v_fmamk_f32 v7, v98, 0x3c800000, v236
	v_mul_f32_e32 v7, 0xbfb8aa3b, v7
	v_fmamk_f32 v13, v103, 0x3c800000, v241
	v_exp_f32_e32 v15, v7
	v_mul_f32_e32 v7, 0xbfb8aa3b, v13
	v_fmamk_f32 v9, v99, 0x3c800000, v237
	v_exp_f32_e32 v17, v7
	v_mul_f32_e32 v7, 0xbfb8aa3b, v9
	v_pk_add_f32 v[8:9], v[10:11], 1.0 op_sel_hi:[1,0]
	v_mul_f32_e32 v6, 0xbfb8aa3b, v6
	v_exp_f32_e32 v6, v6
	v_exp_f32_e32 v7, v7
	v_rcp_f32_e32 v10, v9
	v_pk_add_f32 v[6:7], v[6:7], 1.0 op_sel_hi:[1,0]
	v_rcp_f32_e32 v11, v8
	v_pk_add_f32 v[8:9], v[16:17], 1.0 op_sel_hi:[1,0]
	s_nop 0
	v_rcp_f32_e32 v12, v8
	v_rcp_f32_e32 v13, v9
	v_pk_add_f32 v[8:9], v[14:15], 1.0 op_sel_hi:[1,0]
	s_nop 0
	v_rcp_f32_e32 v9, v9
	v_rcp_f32_e32 v8, v8
	v_rcp_f32_e32 v6, v6
	v_rcp_f32_e32 v7, v7
	s_nop 0
	v_cvt_pk_bf16_f32 v9, v9, v7
	v_cvt_pk_bf16_f32 v8, v8, v6
	v_cvt_pk_bf16_f32 v7, v10, v13
	v_cvt_pk_bf16_f32 v6, v11, v12
	global_store_dwordx4 v[4:5], v[6:9], off offset:256
	s_nop 0
	v_fmamk_f32 v4, v88, 0x3c800000, v226
	v_mul_f32_e32 v4, 0xbfb8aa3b, v4
	v_exp_f32_e32 v12, v4
	v_fmamk_f32 v4, v93, 0x3c800000, v231
	v_mul_f32_e32 v4, 0xbfb8aa3b, v4
	v_fmamk_f32 v8, v92, 0x3c800000, v230
	v_exp_f32_e32 v14, v4
	v_fmamk_f32 v4, v89, 0x3c800000, v227
	v_fmamk_f32 v5, v94, 0x3c800000, v232
	v_mul_f32_e32 v8, 0xbfb8aa3b, v8
	v_mul_f32_e32 v5, 0xbfb8aa3b, v5
	v_exp_f32_e32 v8, v8
	v_exp_f32_e32 v9, v5
	v_fmamk_f32 v5, v90, 0x3c800000, v228
	v_mul_f32_e32 v5, 0xbfb8aa3b, v5
	v_fmamk_f32 v11, v95, 0x3c800000, v233
	v_exp_f32_e32 v13, v5
	v_mul_f32_e32 v5, 0xbfb8aa3b, v11
	v_fmamk_f32 v7, v91, 0x3c800000, v229
	v_exp_f32_e32 v15, v5
	v_mul_f32_e32 v5, 0xbfb8aa3b, v7
	v_pk_add_f32 v[6:7], v[8:9], 1.0 op_sel_hi:[1,0]
	v_mul_f32_e32 v4, 0xbfb8aa3b, v4
	v_exp_f32_e32 v4, v4
	v_exp_f32_e32 v5, v5
	v_rcp_f32_e32 v8, v7
	v_pk_add_f32 v[4:5], v[4:5], 1.0 op_sel_hi:[1,0]
	v_rcp_f32_e32 v9, v6
	v_pk_add_f32 v[6:7], v[14:15], 1.0 op_sel_hi:[1,0]
	s_nop 0
	v_rcp_f32_e32 v10, v6
	v_rcp_f32_e32 v11, v7
	v_pk_add_f32 v[6:7], v[12:13], 1.0 op_sel_hi:[1,0]
	s_nop 0
	v_rcp_f32_e32 v7, v7
	v_rcp_f32_e32 v6, v6
	v_rcp_f32_e32 v4, v4
	s_mov_b64 s[8:9], 0x100000
	v_rcp_f32_e32 v5, v5
	v_bfe_u32 v14, v11, 16, 1
	v_bfe_u32 v15, v10, 16, 1
	v_add3_u32 v10, v10, v15, s33
	v_add3_u32 v11, v11, v14, s33
	v_bfe_u32 v12, v9, 16, 1
	v_bfe_u32 v13, v8, 16, 1
	v_add3_u32 v8, v8, v13, s33
	v_add3_u32 v9, v9, v12, s33
	v_lshrrev_b32_e32 v12, 16, v9
	v_lshrrev_b32_e32 v13, 16, v8
	v_cvt_pk_bf16_f32 v9, v7, v5
	v_cvt_pk_bf16_f32 v8, v6, v4
	v_lshl_add_u64 v[4:5], v[2:3], 0, s[8:9]
	s_mov_b32 s8, 0x100000
	v_and_or_b32 v6, v10, s67, v12
	v_add_co_u32_e32 v10, vcc, s8, v2
	v_and_or_b32 v7, v11, s67, v13
	s_nop 0
	v_addc_co_u32_e32 v11, vcc, 0, v3, vcc
	global_store_dwordx4 v[10:11], v[6:9], off
	s_nop 1
	s_nop 0
	v_fmamk_f32 v6, v80, 0x3c800000, v234
	v_mul_f32_e32 v6, 0xbfb8aa3b, v6
	v_exp_f32_e32 v14, v6
	v_fmamk_f32 v6, v85, 0x3c800000, v239
	v_mul_f32_e32 v6, 0xbfb8aa3b, v6
	v_fmamk_f32 v10, v84, 0x3c800000, v238
	v_exp_f32_e32 v16, v6
	v_fmamk_f32 v6, v81, 0x3c800000, v235
	v_fmamk_f32 v7, v86, 0x3c800000, v240
	v_mul_f32_e32 v10, 0xbfb8aa3b, v10
	v_mul_f32_e32 v7, 0xbfb8aa3b, v7
	v_exp_f32_e32 v10, v10
	v_exp_f32_e32 v11, v7
	v_fmamk_f32 v7, v82, 0x3c800000, v236
	v_mul_f32_e32 v7, 0xbfb8aa3b, v7
	v_fmamk_f32 v13, v87, 0x3c800000, v241
	v_exp_f32_e32 v15, v7
	v_mul_f32_e32 v7, 0xbfb8aa3b, v13
	v_fmamk_f32 v9, v83, 0x3c800000, v237
	v_exp_f32_e32 v17, v7
	v_mul_f32_e32 v7, 0xbfb8aa3b, v9
	v_pk_add_f32 v[8:9], v[10:11], 1.0 op_sel_hi:[1,0]
	v_mul_f32_e32 v6, 0xbfb8aa3b, v6
	v_exp_f32_e32 v6, v6
	v_exp_f32_e32 v7, v7
	v_rcp_f32_e32 v10, v9
	v_pk_add_f32 v[6:7], v[6:7], 1.0 op_sel_hi:[1,0]
	v_rcp_f32_e32 v11, v8
	v_pk_add_f32 v[8:9], v[16:17], 1.0 op_sel_hi:[1,0]
	s_nop 0
	v_rcp_f32_e32 v12, v8
	v_rcp_f32_e32 v13, v9
	v_pk_add_f32 v[8:9], v[14:15], 1.0 op_sel_hi:[1,0]
	s_nop 0
	v_rcp_f32_e32 v9, v9
	v_rcp_f32_e32 v8, v8
	v_rcp_f32_e32 v6, v6
	v_rcp_f32_e32 v7, v7
	s_nop 0
	v_cvt_pk_bf16_f32 v9, v9, v7
	v_cvt_pk_bf16_f32 v8, v8, v6
	v_cvt_pk_bf16_f32 v7, v10, v13
	v_cvt_pk_bf16_f32 v6, v11, v12
	global_store_dwordx4 v[4:5], v[6:9], off offset:256
	s_nop 0
	v_fmamk_f32 v4, v72, 0x3c800000, v226
	v_mul_f32_e32 v4, 0xbfb8aa3b, v4
	v_exp_f32_e32 v12, v4
	v_fmamk_f32 v4, v77, 0x3c800000, v231
	v_mul_f32_e32 v4, 0xbfb8aa3b, v4
	v_fmamk_f32 v8, v76, 0x3c800000, v230
	v_exp_f32_e32 v14, v4
	v_fmamk_f32 v4, v73, 0x3c800000, v227
	v_fmamk_f32 v5, v78, 0x3c800000, v232
	v_mul_f32_e32 v8, 0xbfb8aa3b, v8
	v_mul_f32_e32 v5, 0xbfb8aa3b, v5
	v_exp_f32_e32 v8, v8
	v_exp_f32_e32 v9, v5
	v_fmamk_f32 v5, v74, 0x3c800000, v228
	v_mul_f32_e32 v5, 0xbfb8aa3b, v5
	v_fmamk_f32 v11, v79, 0x3c800000, v233
	v_exp_f32_e32 v13, v5
	v_mul_f32_e32 v5, 0xbfb8aa3b, v11
	v_fmamk_f32 v7, v75, 0x3c800000, v229
	v_exp_f32_e32 v15, v5
	v_mul_f32_e32 v5, 0xbfb8aa3b, v7
	v_pk_add_f32 v[6:7], v[8:9], 1.0 op_sel_hi:[1,0]
	v_mul_f32_e32 v4, 0xbfb8aa3b, v4
	v_exp_f32_e32 v4, v4
	v_exp_f32_e32 v5, v5
	v_rcp_f32_e32 v8, v7
	v_pk_add_f32 v[4:5], v[4:5], 1.0 op_sel_hi:[1,0]
	v_rcp_f32_e32 v9, v6
; __device__ __forceinline__ unsigned pk2(float lo, float hi) { return f2bf(lo) | (f2bf(hi) << 16); }
;     __device__ __forceinline__ void operator()(const f32x4 (&acc)[2][2][4][2], const pg8::Unit& u, int wr, int wc, int fr, int fq) const {
;     ...
;                     } else if constexpr (MODE == 1) {
;                         const f32x4 b0 = *(const f32x4*)(vec + col), b1 = *(const f32x4*)(vec + col + 4);
;                         float r[8];
; #pragma unroll
;                         for (int i = 0; i < 4; ++i) { r[i] = 1.f / (1.f + __expf(-(v0[i] + b0[i]))); r[4 + i] = 1.f / (1.f + __expf(-(v1[i] + b1[i]))); }
;                         u32x4 w; w.x = pk2(r[0], r[1]); w.y = pk2(r[2], r[3]); w.z = pk2(r[4], r[5]); w.w = pk2(r[6], r[7]);
;                         *(u32x4*)(ob + row * 4096 + col) = w;
	v_pk_add_f32 v[6:7], v[14:15], 1.0 op_sel_hi:[1,0]
	s_nop 0
	v_rcp_f32_e32 v10, v6
	v_rcp_f32_e32 v11, v7
	v_pk_add_f32 v[6:7], v[12:13], 1.0 op_sel_hi:[1,0]
	s_nop 0
	v_rcp_f32_e32 v7, v7
	v_rcp_f32_e32 v6, v6
	v_rcp_f32_e32 v4, v4
	s_mov_b64 s[8:9], 0x120000
	v_rcp_f32_e32 v5, v5
	v_bfe_u32 v14, v11, 16, 1
	v_bfe_u32 v15, v10, 16, 1
	v_add3_u32 v10, v10, v15, s33
	v_add3_u32 v11, v11, v14, s33
	v_bfe_u32 v12, v9, 16, 1
	v_bfe_u32 v13, v8, 16, 1
	v_add3_u32 v8, v8, v13, s33
	v_add3_u32 v9, v9, v12, s33
	v_lshrrev_b32_e32 v12, 16, v9
	v_lshrrev_b32_e32 v13, 16, v8
	v_cvt_pk_bf16_f32 v9, v7, v5
	v_cvt_pk_bf16_f32 v8, v6, v4
	v_lshl_add_u64 v[4:5], v[2:3], 0, s[8:9]
	s_mov_b32 s8, 0x120000
	v_and_or_b32 v6, v10, s67, v12
	v_add_co_u32_e32 v10, vcc, s8, v2
	v_and_or_b32 v7, v11, s67, v13
	s_nop 0
	v_addc_co_u32_e32 v11, vcc, 0, v3, vcc
	global_store_dwordx4 v[10:11], v[6:9], off
	s_nop 1
	s_nop 0
	v_fmamk_f32 v6, v64, 0x3c800000, v234
	v_mul_f32_e32 v6, 0xbfb8aa3b, v6
	v_exp_f32_e32 v14, v6
	v_fmamk_f32 v6, v69, 0x3c800000, v239
	v_mul_f32_e32 v6, 0xbfb8aa3b, v6
	v_fmamk_f32 v10, v68, 0x3c800000, v238
	v_exp_f32_e32 v16, v6
	v_fmamk_f32 v6, v65, 0x3c800000, v235
	v_fmamk_f32 v7, v70, 0x3c800000, v240
	v_mul_f32_e32 v10, 0xbfb8aa3b, v10
	v_mul_f32_e32 v7, 0xbfb8aa3b, v7
	v_exp_f32_e32 v10, v10
	v_exp_f32_e32 v11, v7
	v_fmamk_f32 v7, v66, 0x3c800000, v236
	v_mul_f32_e32 v7, 0xbfb8aa3b, v7
	v_fmamk_f32 v13, v71, 0x3c800000, v241
	v_exp_f32_e32 v15, v7
	v_mul_f32_e32 v7, 0xbfb8aa3b, v13
	v_fmamk_f32 v9, v67, 0x3c800000, v237
	v_exp_f32_e32 v17, v7
	v_mul_f32_e32 v7, 0xbfb8aa3b, v9
	v_pk_add_f32 v[8:9], v[10:11], 1.0 op_sel_hi:[1,0]
	v_mul_f32_e32 v6, 0xbfb8aa3b, v6
	v_exp_f32_e32 v6, v6
	v_exp_f32_e32 v7, v7
	v_rcp_f32_e32 v10, v9
	v_pk_add_f32 v[6:7], v[6:7], 1.0 op_sel_hi:[1,0]
	v_rcp_f32_e32 v11, v8
	v_pk_add_f32 v[8:9], v[16:17], 1.0 op_sel_hi:[1,0]
	s_nop 0
	v_rcp_f32_e32 v12, v8
	v_rcp_f32_e32 v13, v9
	v_pk_add_f32 v[8:9], v[14:15], 1.0 op_sel_hi:[1,0]
	s_nop 0
	v_rcp_f32_e32 v9, v9
	v_rcp_f32_e32 v8, v8
	v_rcp_f32_e32 v6, v6
	v_rcp_f32_e32 v7, v7
	s_nop 0
	v_cvt_pk_bf16_f32 v9, v9, v7
	v_cvt_pk_bf16_f32 v8, v8, v6
	v_cvt_pk_bf16_f32 v7, v10, v13
	v_cvt_pk_bf16_f32 v6, v11, v12
	global_store_dwordx4 v[4:5], v[6:9], off offset:256
	s_nop 0
	v_fmamk_f32 v4, v56, 0x3c800000, v226
	v_mul_f32_e32 v4, 0xbfb8aa3b, v4
	v_exp_f32_e32 v12, v4
	v_fmamk_f32 v4, v61, 0x3c800000, v231
	v_mul_f32_e32 v4, 0xbfb8aa3b, v4
	v_fmamk_f32 v8, v60, 0x3c800000, v230
	v_exp_f32_e32 v14, v4
	v_fmamk_f32 v4, v57, 0x3c800000, v227
	v_fmamk_f32 v5, v62, 0x3c800000, v232
	v_mul_f32_e32 v8, 0xbfb8aa3b, v8
	v_mul_f32_e32 v5, 0xbfb8aa3b, v5
	v_exp_f32_e32 v8, v8
	v_exp_f32_e32 v9, v5
	v_fmamk_f32 v5, v58, 0x3c800000, v228
	v_mul_f32_e32 v5, 0xbfb8aa3b, v5
	v_fmamk_f32 v11, v63, 0x3c800000, v233
	v_exp_f32_e32 v13, v5
	v_mul_f32_e32 v5, 0xbfb8aa3b, v11
	v_fmamk_f32 v7, v59, 0x3c800000, v229
	v_exp_f32_e32 v15, v5
	v_mul_f32_e32 v5, 0xbfb8aa3b, v7
	v_pk_add_f32 v[6:7], v[8:9], 1.0 op_sel_hi:[1,0]
	v_mul_f32_e32 v4, 0xbfb8aa3b, v4
	v_exp_f32_e32 v4, v4
	v_exp_f32_e32 v5, v5
	v_rcp_f32_e32 v8, v7
	v_pk_add_f32 v[4:5], v[4:5], 1.0 op_sel_hi:[1,0]
	v_rcp_f32_e32 v9, v6
	v_pk_add_f32 v[6:7], v[14:15], 1.0 op_sel_hi:[1,0]
	s_nop 0
	v_rcp_f32_e32 v10, v6
	v_rcp_f32_e32 v11, v7
	v_pk_add_f32 v[6:7], v[12:13], 1.0 op_sel_hi:[1,0]
	s_nop 0
	v_rcp_f32_e32 v7, v7
	v_rcp_f32_e32 v6, v6
	v_rcp_f32_e32 v4, v4
	s_mov_b64 s[8:9], 0x140000
	v_rcp_f32_e32 v5, v5
	v_bfe_u32 v14, v11, 16, 1
	v_bfe_u32 v15, v10, 16, 1
	v_add3_u32 v10, v10, v15, s33
	v_add3_u32 v11, v11, v14, s33
	v_bfe_u32 v12, v9, 16, 1
	v_bfe_u32 v13, v8, 16, 1
	v_add3_u32 v8, v8, v13, s33
	v_add3_u32 v9, v9, v12, s33
	v_lshrrev_b32_e32 v12, 16, v9
	v_lshrrev_b32_e32 v13, 16, v8
	v_cvt_pk_bf16_f32 v9, v7, v5
	v_cvt_pk_bf16_f32 v8, v6, v4
	v_lshl_add_u64 v[4:5], v[2:3], 0, s[8:9]
	s_mov_b32 s8, 0x140000
	v_and_or_b32 v6, v10, s67, v12
	v_add_co_u32_e32 v10, vcc, s8, v2
	v_and_or_b32 v7, v11, s67, v13
	s_nop 0
	v_addc_co_u32_e32 v11, vcc, 0, v3, vcc
	global_store_dwordx4 v[10:11], v[6:9], off
	s_nop 1
	s_nop 0
	v_fmamk_f32 v6, v48, 0x3c800000, v234
	v_mul_f32_e32 v6, 0xbfb8aa3b, v6
	v_exp_f32_e32 v14, v6
	v_fmamk_f32 v6, v53, 0x3c800000, v239
	v_mul_f32_e32 v6, 0xbfb8aa3b, v6
	v_fmamk_f32 v10, v52, 0x3c800000, v238
	v_exp_f32_e32 v16, v6
	v_fmamk_f32 v6, v49, 0x3c800000, v235
	v_fmamk_f32 v7, v54, 0x3c800000, v240
	v_mul_f32_e32 v10, 0xbfb8aa3b, v10
	v_mul_f32_e32 v7, 0xbfb8aa3b, v7
	v_exp_f32_e32 v10, v10
	v_exp_f32_e32 v11, v7
	v_fmamk_f32 v7, v50, 0x3c800000, v236
	v_mul_f32_e32 v7, 0xbfb8aa3b, v7
	v_fmamk_f32 v13, v55, 0x3c800000, v241
	v_exp_f32_e32 v15, v7
	v_mul_f32_e32 v7, 0xbfb8aa3b, v13
	v_fmamk_f32 v9, v51, 0x3c800000, v237
	v_exp_f32_e32 v17, v7
	v_mul_f32_e32 v7, 0xbfb8aa3b, v9
; #define PG8_BAR __builtin_amdgcn_s_barrier()
; __device__ __forceinline__ unsigned pk2(float lo, float hi) { return f2bf(lo) | (f2bf(hi) << 16); }
; template <class Epi, class Sched, bool ALIGN_EPI = false, bool SP2 = false, bool F8 = false>
; __device__ __forceinline__ void gemm_phase(PG8_LAS unsigned char* lds, const Gemm g, const Sched& S, const Epi& E) {
;     ...
;         cur = nxt; cA = nA; cB = nB; ++ui;
;         if constexpr (ALIGN_EPI) { if (wr == 1) PG8_BAR; }
;     __device__ __forceinline__ void operator()(const f32x4 (&acc)[2][2][4][2], const pg8::Unit& u, int wr, int wc, int fr, int fq) const {
;     ...
;                     } else if constexpr (MODE == 1) {
;                         const f32x4 b0 = *(const f32x4*)(vec + col), b1 = *(const f32x4*)(vec + col + 4);
;                         float r[8];
; #pragma unroll
;                         for (int i = 0; i < 4; ++i) { r[i] = 1.f / (1.f + __expf(-(v0[i] + b0[i]))); r[4 + i] = 1.f / (1.f + __expf(-(v1[i] + b1[i]))); }
;                         u32x4 w; w.x = pk2(r[0], r[1]); w.y = pk2(r[2], r[3]); w.z = pk2(r[4], r[5]); w.w = pk2(r[6], r[7]);
;                         *(u32x4*)(ob + row * 4096 + col) = w;
	v_pk_add_f32 v[8:9], v[10:11], 1.0 op_sel_hi:[1,0]
	v_mul_f32_e32 v6, 0xbfb8aa3b, v6
	v_exp_f32_e32 v6, v6
	v_exp_f32_e32 v7, v7
	v_rcp_f32_e32 v10, v9
	v_pk_add_f32 v[6:7], v[6:7], 1.0 op_sel_hi:[1,0]
	v_rcp_f32_e32 v11, v8
	v_pk_add_f32 v[8:9], v[16:17], 1.0 op_sel_hi:[1,0]
	s_nop 0
	v_rcp_f32_e32 v12, v8
	v_rcp_f32_e32 v13, v9
	v_pk_add_f32 v[8:9], v[14:15], 1.0 op_sel_hi:[1,0]
	s_nop 0
	v_rcp_f32_e32 v9, v9
	v_rcp_f32_e32 v8, v8
	v_rcp_f32_e32 v6, v6
	v_div_scale_f32 v14, s[8:9], v7, v7, 1.0
	v_rcp_f32_e32 v15, v14
	s_nop 0
	v_fma_f32 v16, -v14, v15, 1.0
	v_fmac_f32_e32 v15, v16, v15
	v_div_scale_f32 v16, vcc, 1.0, v7, 1.0
	v_mul_f32_e32 v17, v16, v15
	v_fma_f32 v18, -v14, v17, v16
	v_fmac_f32_e32 v17, v18, v15
	v_rcp_f32_e32 v7, v7
	s_nop 0
	v_cvt_pk_bf16_f32 v9, v9, v7
	v_cvt_pk_bf16_f32 v8, v8, v6
	v_cvt_pk_bf16_f32 v7, v10, v13
	v_cvt_pk_bf16_f32 v6, v11, v12
	global_store_dwordx4 v[4:5], v[6:9], off offset:256
	s_nop 0
	v_fmamk_f32 v4, v40, 0x3c800000, v226
	v_mul_f32_e32 v4, 0xbfb8aa3b, v4
	v_exp_f32_e32 v12, v4
	v_fmamk_f32 v4, v45, 0x3c800000, v231
	v_mul_f32_e32 v4, 0xbfb8aa3b, v4
	v_fmamk_f32 v8, v44, 0x3c800000, v230
	v_exp_f32_e32 v14, v4
	v_fmamk_f32 v4, v41, 0x3c800000, v227
	v_fmamk_f32 v5, v46, 0x3c800000, v232
	v_mul_f32_e32 v8, 0xbfb8aa3b, v8
	v_mul_f32_e32 v5, 0xbfb8aa3b, v5
	v_exp_f32_e32 v8, v8
	v_exp_f32_e32 v9, v5
	v_fmamk_f32 v5, v42, 0x3c800000, v228
	v_mul_f32_e32 v5, 0xbfb8aa3b, v5
	v_fmamk_f32 v11, v47, 0x3c800000, v233
	v_exp_f32_e32 v13, v5
	v_mul_f32_e32 v5, 0xbfb8aa3b, v11
	v_fmamk_f32 v7, v43, 0x3c800000, v229
	v_exp_f32_e32 v15, v5
	v_mul_f32_e32 v5, 0xbfb8aa3b, v7
	v_pk_add_f32 v[6:7], v[8:9], 1.0 op_sel_hi:[1,0]
	v_mul_f32_e32 v4, 0xbfb8aa3b, v4
	v_exp_f32_e32 v4, v4
	v_exp_f32_e32 v5, v5
	v_rcp_f32_e32 v8, v7
	v_pk_add_f32 v[4:5], v[4:5], 1.0 op_sel_hi:[1,0]
	v_rcp_f32_e32 v9, v6
	v_pk_add_f32 v[6:7], v[14:15], 1.0 op_sel_hi:[1,0]
	s_nop 0
	v_rcp_f32_e32 v10, v6
	v_rcp_f32_e32 v11, v7
	v_pk_add_f32 v[6:7], v[12:13], 1.0 op_sel_hi:[1,0]
	s_nop 0
	v_rcp_f32_e32 v7, v7
	v_rcp_f32_e32 v6, v6
	v_rcp_f32_e32 v4, v4
	v_div_scale_f32 v12, s[8:9], v5, v5, 1.0
	v_rcp_f32_e32 v13, v12
	s_mov_b64 s[8:9], 0x160000
	v_fma_f32 v14, -v12, v13, 1.0
	v_fmac_f32_e32 v13, v14, v13
	v_div_scale_f32 v14, vcc, 1.0, v5, 1.0
	v_mul_f32_e32 v15, v14, v13
	v_fma_f32 v16, -v12, v15, v14
	v_rcp_f32_e32 v5, v5
	v_bfe_u32 v14, v11, 16, 1
	v_bfe_u32 v15, v10, 16, 1
	v_add3_u32 v10, v10, v15, s33
	v_add3_u32 v11, v11, v14, s33
	v_bfe_u32 v12, v9, 16, 1
	v_bfe_u32 v13, v8, 16, 1
	v_add3_u32 v8, v8, v13, s33
	v_add3_u32 v9, v9, v12, s33
	v_lshrrev_b32_e32 v12, 16, v9
	v_lshrrev_b32_e32 v13, 16, v8
	v_cvt_pk_bf16_f32 v9, v7, v5
	v_cvt_pk_bf16_f32 v8, v6, v4
	v_lshl_add_u64 v[4:5], v[2:3], 0, s[8:9]
	s_mov_b32 s8, 0x160000
	v_add_co_u32_e32 v2, vcc, s8, v2
	v_and_or_b32 v7, v11, s67, v13
	v_and_or_b32 v6, v10, s67, v12
	v_addc_co_u32_e32 v3, vcc, 0, v3, vcc
	global_store_dwordx4 v[2:3], v[6:9], off
	s_nop 1
	s_nop 0
	v_fmamk_f32 v9, v35, 0x3c800000, v237
	v_fmamk_f32 v0, v36, 0x3c800000, v238
	v_mul_f32_e32 v0, 0xbfb8aa3b, v0
	v_exp_f32_e32 v10, v0
	v_fmamk_f32 v0, v32, 0x3c800000, v234
	v_mul_f32_e32 v0, 0xbfb8aa3b, v0
	v_exp_f32_e32 v6, v0
	v_fmamk_f32 v0, v37, 0x3c800000, v239
	v_fmamk_f32 v1, v38, 0x3c800000, v240
	v_mul_f32_e32 v1, 0xbfb8aa3b, v1
	v_exp_f32_e32 v11, v1
	v_fmamk_f32 v1, v34, 0x3c800000, v236
	v_mul_f32_e32 v0, 0xbfb8aa3b, v0
	v_mul_f32_e32 v1, 0xbfb8aa3b, v1
	v_fmamk_f32 v3, v39, 0x3c800000, v241
	v_exp_f32_e32 v12, v0
	v_fmamk_f32 v0, v33, 0x3c800000, v235
	v_exp_f32_e32 v7, v1
	v_mul_f32_e32 v1, 0xbfb8aa3b, v3
	v_pk_add_f32 v[2:3], v[10:11], 1.0 op_sel_hi:[1,0]
	v_exp_f32_e32 v13, v1
	v_mul_f32_e32 v1, 0xbfb8aa3b, v9
	v_mul_f32_e32 v0, 0xbfb8aa3b, v0
	v_exp_f32_e32 v0, v0
	v_exp_f32_e32 v1, v1
	v_rcp_f32_e32 v8, v3
	v_pk_add_f32 v[0:1], v[0:1], 1.0 op_sel_hi:[1,0]
	v_rcp_f32_e32 v9, v2
	v_pk_add_f32 v[2:3], v[12:13], 1.0 op_sel_hi:[1,0]
	s_nop 0
	v_rcp_f32_e32 v10, v2
	v_rcp_f32_e32 v11, v3
	v_pk_add_f32 v[2:3], v[6:7], 1.0 op_sel_hi:[1,0]
	s_nop 0
	v_rcp_f32_e32 v3, v3
	v_rcp_f32_e32 v2, v2
	v_rcp_f32_e32 v0, v0
	v_div_scale_f32 v6, s[8:9], v1, v1, 1.0
	v_rcp_f32_e32 v7, v6
	s_nop 0
	v_fma_f32 v12, -v6, v7, 1.0
	v_fmac_f32_e32 v7, v12, v7
	v_div_scale_f32 v12, vcc, 1.0, v1, 1.0
	v_mul_f32_e32 v13, v12, v7
	v_fma_f32 v14, -v6, v13, v12
	v_fmac_f32_e32 v13, v14, v7
	v_fma_f32 v6, -v6, v13, v12
	v_div_fmas_f32 v6, v6, v7, v13
	v_rcp_f32_e32 v1, v1
	s_nop 0
	v_cvt_pk_bf16_f32 v3, v3, v1
	v_cvt_pk_bf16_f32 v2, v2, v0
	v_cvt_pk_bf16_f32 v1, v8, v11
	v_cvt_pk_bf16_f32 v0, v9, v10
	s_andn2_b64 vcc, exec, s[38:39]
	global_store_dwordx4 v[4:5], v[0:3], off offset:256
	s_cbranch_vccnz .LBB0_1114
	s_andn2_b64 vcc, exec, s[0:1]
	s_cbranch_vccnz .LBB0_1113
	s_barrier
	s_branch .LBB0_1113
